# LN fix-up passes: gamma/beta loads issued once before the row loop (loop invariant), store groups no longer wait on vmcnt(0) behind the previous store
# baseline (speedup 1.0000x reference)
.LBB0_1832:
	s_mov_b64 s[12:13], s[74:75]
	s_waitcnt lgkmcnt(0)
	s_barrier
	v_mbcnt_lo_u32_b32 v0, -1, 0
	v_mbcnt_hi_u32_b32 v0, -1, v0
	v_readlane_b32 s2, v251, 5
	s_nop 1
	v_add_u32_e32 v0, s2, v0
	v_readlane_b32 s2, v251, 4
	s_nop 0
	v_ashrrev_i32_e32 v1, 6, v0
	v_add_u32_e32 v8, s2, v1
	s_movk_i32 s2, 0x200
	v_cmp_gt_i32_e32 vcc, s2, v8
	s_and_saveexec_b64 s[16:17], vcc
	s_movk_i32 s18, 0x1ff
	s_mov_b32 s28, 0x800000
	s_mov_b32 s29, 0x200000
	s_mov_b32 s31, 0x400000
	s_mov_b32 s38, 0x600000
	s_cbranch_execz .LBB0_1835
	s_load_dwordx4 s[44:47], s[12:13], 0xd0
	s_load_dwordx2 s[2:3], s[12:13], 0x110
	s_lshl_b64 s[6:7], s[86:87], 2
	v_lshlrev_b32_e32 v0, 2, v0
	v_and_b32_e32 v2, 0xfc, v0
	s_waitcnt lgkmcnt(0)
	s_add_u32 s12, s46, s6
	s_addc_u32 s13, s47, s7
	s_add_u32 s6, s44, s6
	s_addc_u32 s7, s45, s7
	v_lshlrev_b32_e32 v0, 2, v2
	v_mov_b32_e32 v1, v64
	v_lshlrev_b32_e32 v2, 1, v2
	v_mov_b32_e32 v3, v64
	v_lshl_add_u64 v[10:11], s[6:7], 0, v[0:1]
	v_lshl_add_u64 v[12:13], s[12:13], 0, v[0:1]
	v_lshl_add_u64 v[2:3], s[2:3], 0, v[2:3]
	s_mov_b64 s[6:7], 0x8000000
	v_lshl_add_u64 v[0:1], s[2:3], 0, v[0:1]
	s_mov_b64 s[2:3], 0x18500000
	v_lshl_add_u64 v[14:15], v[2:3], 0, s[6:7]
	v_lshl_add_u64 v[16:17], v[0:1], 0, s[2:3]
	s_mov_b64 s[20:21], 0
	global_load_dwordx4 v[164:167], v[10:11], off
	global_load_dwordx4 v[168:171], v[12:13], off
	global_load_dwordx4 v[172:175], v[10:11], off offset:1024
	global_load_dwordx4 v[176:179], v[12:13], off offset:1024
	global_load_dwordx4 v[180:183], v[10:11], off offset:2048
	global_load_dwordx4 v[184:187], v[12:13], off offset:2048
	global_load_dwordx4 v[188:191], v[10:11], off offset:3072
	global_load_dwordx4 v[192:195], v[12:13], off offset:3072
.LBB0_1834:
	v_ashrrev_i32_e32 v9, 31, v8
	v_lshlrev_b64 v[0:1], 11, v[8:9]
	v_lshl_add_u64 v[18:19], v[14:15], 0, v[0:1]
	global_load_dwordx2 v[68:69], v[18:19], off
	v_lshlrev_b64 v[2:3], 12, v[8:9]
	v_lshl_add_u64 v[36:37], v[16:17], 0, v[2:3]
	global_load_dwordx4 v[72:75], v[36:37], off
	v_add_co_u32_e32 v30, vcc, s29, v36
	v_add_u32_e32 v8, s73, v8
	s_nop 0
	v_addc_co_u32_e32 v31, vcc, 0, v37, vcc
	global_load_dwordx4 v[76:79], v[30:31], off
	v_add_co_u32_e32 v28, vcc, s31, v36
	s_waitcnt vmcnt(2)
	v_lshlrev_b32_e32 v4, 16, v68
	v_and_b32_e32 v5, 0xffff0000, v68
	v_lshlrev_b32_e32 v6, 16, v69
	v_and_b32_e32 v7, 0xffff0000, v69
	v_addc_co_u32_e32 v29, vcc, 0, v37, vcc
	global_load_dwordx4 v[80:83], v[28:29], off
	s_waitcnt vmcnt(2)
	v_pk_fma_f32 v[6:7], v[6:7], s[94:95], v[74:75] op_sel_hi:[1,0,1]
	v_pk_fma_f32 v[4:5], v[4:5], s[94:95], v[72:73] op_sel_hi:[1,0,1]
	s_waitcnt vmcnt(1)
	v_pk_add_f32 v[6:7], v[6:7], v[78:79]
	v_pk_add_f32 v[4:5], v[4:5], v[76:77]
	s_waitcnt vmcnt(0)
	v_pk_add_f32 v[20:21], v[6:7], v[82:83]
	v_add_co_u32_e32 v6, vcc, s38, v36
	v_pk_add_f32 v[22:23], v[4:5], v[80:81]
	s_nop 0
	v_addc_co_u32_e32 v7, vcc, 0, v37, vcc
	global_load_dwordx4 v[84:87], v[6:7], off
	global_load_dwordx2 v[88:89], v[18:19], off offset:512
	global_load_dwordx4 v[92:95], v[36:37], off offset:1024
	global_load_dwordx4 v[96:99], v[30:31], off offset:1024
	global_load_dwordx4 v[100:103], v[28:29], off offset:1024
	global_load_dwordx4 v[104:107], v[6:7], off offset:1024
	global_load_dwordx2 v[108:109], v[18:19], off offset:1024
	global_load_dwordx4 v[112:115], v[36:37], off offset:2048
	global_load_dwordx4 v[116:119], v[30:31], off offset:2048
	global_load_dwordx4 v[120:123], v[28:29], off offset:2048
	global_load_dwordx4 v[124:127], v[6:7], off offset:2048
	global_load_dwordx2 v[128:129], v[18:19], off offset:1536
	global_load_dwordx4 v[132:135], v[36:37], off offset:3072
	global_load_dwordx4 v[136:139], v[30:31], off offset:3072
	global_load_dwordx4 v[140:143], v[28:29], off offset:3072
	global_load_dwordx4 v[144:147], v[6:7], off offset:3072
	s_waitcnt vmcnt(15)
	v_pk_add_f32 v[0:1], v[20:21], v[86:87]
	v_pk_add_f32 v[2:3], v[22:23], v[84:85]
	s_waitcnt vmcnt(14)
	v_lshlrev_b32_e32 v24, 16, v88
	v_and_b32_e32 v25, 0xffff0000, v88
	v_lshlrev_b32_e32 v4, 16, v89
	v_and_b32_e32 v5, 0xffff0000, v89
	s_waitcnt vmcnt(13)
	v_pk_fma_f32 v[4:5], v[4:5], s[94:95], v[94:95] op_sel_hi:[1,0,1]
	v_pk_fma_f32 v[24:25], v[24:25], s[94:95], v[92:93] op_sel_hi:[1,0,1]
	s_waitcnt vmcnt(12)
	v_pk_add_f32 v[4:5], v[4:5], v[98:99]
	v_pk_add_f32 v[24:25], v[24:25], v[96:97]
	s_waitcnt vmcnt(11)
	v_pk_add_f32 v[4:5], v[4:5], v[102:103]
	v_pk_add_f32 v[26:27], v[24:25], v[100:101]
	s_waitcnt vmcnt(10)
	v_pk_add_f32 v[20:21], v[4:5], v[106:107]
	v_pk_mov_b32 v[4:5], v[2:3], v[0:1] op_sel:[1,0]
	v_mov_b32_e32 v24, v2
	v_mov_b32_e32 v25, v1
	v_pk_add_f32 v[4:5], v[4:5], v[24:25]
	v_pk_add_f32 v[22:23], v[26:27], v[104:105]
	v_add_f32_e32 v4, v4, v5
	v_add_f32_e32 v4, 0, v4
	s_waitcnt vmcnt(9)
	v_lshlrev_b32_e32 v32, 16, v108
	v_and_b32_e32 v33, 0xffff0000, v108
	v_lshlrev_b32_e32 v34, 16, v109
	v_and_b32_e32 v35, 0xffff0000, v109
	s_waitcnt vmcnt(8)
	v_pk_fma_f32 v[34:35], v[34:35], s[94:95], v[114:115] op_sel_hi:[1,0,1]
	v_pk_fma_f32 v[32:33], v[32:33], s[94:95], v[112:113] op_sel_hi:[1,0,1]
	s_waitcnt vmcnt(7)
	v_pk_add_f32 v[34:35], v[34:35], v[118:119]
	v_pk_add_f32 v[32:33], v[32:33], v[116:117]
	s_waitcnt vmcnt(6)
	v_pk_add_f32 v[26:27], v[34:35], v[122:123]
	v_pk_add_f32 v[38:39], v[32:33], v[120:121]
	s_waitcnt vmcnt(5)
	v_pk_add_f32 v[24:25], v[26:27], v[126:127]
	v_pk_add_f32 v[26:27], v[38:39], v[124:125]
	v_pk_mov_b32 v[32:33], v[22:23], v[20:21] op_sel:[1,0]
	v_mov_b32_e32 v34, v22
	v_mov_b32_e32 v35, v21
	v_pk_add_f32 v[32:33], v[32:33], v[34:35]
	s_waitcnt vmcnt(4)
	v_lshlrev_b32_e32 v40, 16, v128
	v_and_b32_e32 v41, 0xffff0000, v128
	v_lshlrev_b32_e32 v42, 16, v129
	v_and_b32_e32 v43, 0xffff0000, v129
	v_pk_add_f32 v[34:35], v[32:33], v[32:33] op_sel:[0,1] op_sel_hi:[1,0]
	v_add_f32_e32 v32, v24, v25
	s_waitcnt vmcnt(3)
	v_pk_fma_f32 v[42:43], v[42:43], s[94:95], v[134:135] op_sel_hi:[1,0,1]
	v_pk_fma_f32 v[40:41], v[40:41], s[94:95], v[132:133] op_sel_hi:[1,0,1]
	s_waitcnt vmcnt(2)
	v_pk_add_f32 v[38:39], v[42:43], v[138:139]
	v_pk_add_f32 v[36:37], v[40:41], v[136:137]
	s_waitcnt vmcnt(1)
	v_pk_add_f32 v[30:31], v[38:39], v[142:143]
	v_pk_add_f32 v[40:41], v[36:37], v[140:141]
	v_add_f32_e32 v6, v26, v27
	s_waitcnt vmcnt(0)
	v_pk_add_f32 v[28:29], v[30:31], v[146:147]
	v_pk_add_f32 v[30:31], v[40:41], v[144:145]
	v_mov_b32_e32 v7, v28
	v_mov_b32_e32 v5, v30
	v_mov_b32_e32 v35, v31
	v_mov_b32_e32 v33, v29
	v_pk_add_f32 v[4:5], v[4:5], v[34:35]
	v_pk_add_f32 v[6:7], v[6:7], v[32:33]
	s_nop 0
	v_pk_add_f32 v[4:5], v[4:5], v[6:7]
	s_nop 0
	v_add_f32_e32 v4, v4, v5
	s_nop 1
	v_add_f32_dpp v4, v4, v4 quad_perm:[1,0,3,2] row_mask:0xf bank_mask:0xf bound_ctrl:1
	s_nop 1
	v_add_f32_dpp v4, v4, v4 quad_perm:[2,3,0,1] row_mask:0xf bank_mask:0xf bound_ctrl:1
	s_nop 1
	v_add_f32_dpp v4, v4, v4 row_half_mirror row_mask:0xf bank_mask:0xf bound_ctrl:1
	s_nop 1
	v_add_f32_dpp v4, v4, v4 row_mirror row_mask:0xf bank_mask:0xf bound_ctrl:1
	s_nop 0
	v_readlane_b32 s6, v4, 16
	v_readlane_b32 s7, v4, 48
	v_readlane_b32 s2, v4, 0
	v_readlane_b32 s3, v4, 32
	v_mov_b32_e32 v4, s6
	v_mov_b32_e32 v5, s7
	v_pk_add_f32 v[4:5], s[2:3], v[4:5]
	s_nop 0
	v_add_f32_e32 v9, v4, v5
	v_fmamk_f32 v3, v9, 0xba800000, v3
	v_fmac_f32_e32 v2, 0xba800000, v9
	v_fmamk_f32 v1, v9, 0xba800000, v1
	v_fmac_f32_e32 v0, 0xba800000, v9
	v_pk_mul_f32 v[4:5], v[0:1], v[0:1]
	v_pk_mul_f32 v[6:7], v[2:3], v[2:3]
	v_fmamk_f32 v23, v9, 0xba800000, v23
	v_pk_mov_b32 v[32:33], v[6:7], v[4:5] op_sel:[1,0]
	v_mov_b32_e32 v7, v5
	v_pk_add_f32 v[4:5], v[32:33], v[6:7]
	v_fmac_f32_e32 v22, 0xba800000, v9
	v_fmamk_f32 v21, v9, 0xba800000, v21
	v_fmac_f32_e32 v20, 0xba800000, v9
	v_pk_add_f32 v[4:5], v[4:5], v[4:5] op_sel_hi:[0,1]
	v_pk_mul_f32 v[6:7], v[20:21], v[20:21]
	v_pk_mul_f32 v[32:33], v[22:23], v[22:23]
	v_fmac_f32_e32 v26, 0xba800000, v9
	v_pk_mov_b32 v[34:35], v[32:33], v[6:7] op_sel:[1,0]
	v_mov_b32_e32 v33, v7
	v_fmamk_f32 v27, v9, 0xba800000, v27
	v_fmac_f32_e32 v24, 0xba800000, v9
	v_mul_f32_e32 v4, v26, v26
	v_pk_add_f32 v[6:7], v[34:35], v[32:33]
	v_fmamk_f32 v25, v9, 0xba800000, v25
	v_pk_fma_f32 v[32:33], v[26:27], v[26:27], v[4:5] op_sel_hi:[1,1,0]
	v_mul_f32_e32 v4, v24, v24
	v_pk_add_f32 v[6:7], v[6:7], v[6:7] op_sel_hi:[0,1]
	v_pk_fma_f32 v[34:35], v[24:25], v[24:25], v[4:5] op_sel_hi:[1,1,0]
	v_fmamk_f32 v29, v9, 0xba800000, v29
	v_fmac_f32_e32 v28, 0xba800000, v9
	v_fmamk_f32 v31, v9, 0xba800000, v31
	v_fmac_f32_e32 v30, 0xba800000, v9
	v_mul_f32_e32 v32, v30, v30
	v_mul_f32_e32 v34, v31, v31
	v_mul_f32_e32 v4, v28, v28
	v_mul_f32_e32 v6, v29, v29
	v_pk_add_f32 v[32:33], v[32:33], v[34:35]
	v_pk_add_f32 v[4:5], v[4:5], v[6:7]
	s_nop 0
	v_pk_add_f32 v[4:5], v[32:33], v[4:5]
	s_nop 0
	v_add_f32_e32 v4, v4, v5
	s_nop 1
	v_add_f32_dpp v4, v4, v4 quad_perm:[1,0,3,2] row_mask:0xf bank_mask:0xf bound_ctrl:1
	s_nop 1
	v_add_f32_dpp v4, v4, v4 quad_perm:[2,3,0,1] row_mask:0xf bank_mask:0xf bound_ctrl:1
	s_nop 1
	v_add_f32_dpp v4, v4, v4 row_half_mirror row_mask:0xf bank_mask:0xf bound_ctrl:1
	s_nop 1
	v_add_f32_dpp v4, v4, v4 row_mirror row_mask:0xf bank_mask:0xf bound_ctrl:1
	s_nop 0
	v_readlane_b32 s6, v4, 16
	v_readlane_b32 s7, v4, 48
	v_readlane_b32 s2, v4, 0
	v_readlane_b32 s3, v4, 32
	v_mov_b32_e32 v4, s6
	v_mov_b32_e32 v5, s7
	v_pk_add_f32 v[4:5], s[2:3], v[4:5]
	s_nop 0
	v_add_f32_e32 v4, v4, v5
	v_fmamk_f32 v4, v4, 0x3a800000, v213
	v_cmp_gt_f32_e32 vcc, s28, v4
	v_mul_f32_e32 v5, 0x4b800000, v4
	s_nop 0
	v_cndmask_b32_e32 v4, v4, v5, vcc
	v_rsq_f32_e32 v4, v4
	s_nop 0
	v_mul_f32_e32 v5, 0x45800000, v4
	v_cndmask_b32_e32 v32, v4, v5, vcc
	v_pk_mul_f32 v[34:35], v[2:3], v[32:33] op_sel_hi:[1,0]
	v_pk_mul_f32 v[36:37], v[0:1], v[32:33] op_sel_hi:[1,0]
	v_mov_b32_e32 v38, v146
	v_mov_b32_e32 v39, v147


	v_pk_mul_f32 v[22:23], v[22:23], v[32:33] op_sel_hi:[1,0]
	v_pk_mul_f32 v[20:21], v[20:21], v[32:33] op_sel_hi:[1,0]
	v_cmp_lt_i32_e32 vcc, s18, v8
	s_or_b64 s[20:21], vcc, s[20:21]
	s_waitcnt vmcnt(0)
	v_pk_fma_f32 v[2:3], v[166:167], v[36:37], v[170:171]
	v_pk_fma_f32 v[0:1], v[164:165], v[34:35], v[168:169]
	s_nop 0
	v_cvt_pk_bf16_f32 v0, v0, v1
	v_cvt_pk_bf16_f32 v1, v2, v3
	global_store_dwordx2 v[18:19], v[0:1], off

	s_nop 0


	v_pk_fma_f32 v[2:3], v[174:175], v[20:21], v[178:179]
	v_pk_fma_f32 v[0:1], v[172:173], v[22:23], v[176:177]
	v_pk_mul_f32 v[20:21], v[26:27], v[32:33] op_sel_hi:[1,0]
	v_cvt_pk_bf16_f32 v0, v0, v1
	v_cvt_pk_bf16_f32 v1, v2, v3
	global_store_dwordx2 v[18:19], v[0:1], off offset:512

	s_nop 0

	v_pk_mul_f32 v[22:23], v[24:25], v[32:33] op_sel_hi:[1,0]

	v_pk_fma_f32 v[0:1], v[180:181], v[20:21], v[184:185]
	v_pk_fma_f32 v[2:3], v[182:183], v[22:23], v[186:187]
	v_cvt_pk_bf16_f32 v0, v0, v1
	v_cvt_pk_bf16_f32 v1, v2, v3
	global_store_dwordx2 v[18:19], v[0:1], off offset:1024

	s_nop 0

	v_pk_mul_f32 v[20:21], v[30:31], v[32:33] op_sel_hi:[1,0]
	v_pk_mul_f32 v[22:23], v[28:29], v[32:33] op_sel_hi:[1,0]

	v_pk_fma_f32 v[0:1], v[188:189], v[20:21], v[192:193]
	v_pk_fma_f32 v[2:3], v[190:191], v[22:23], v[194:195]
	v_cvt_pk_bf16_f32 v0, v0, v1
	v_cvt_pk_bf16_f32 v1, v2, v3
	global_store_dwordx2 v[18:19], v[0:1], off offset:1536
	s_andn2_b64 exec, exec, s[20:21]
	s_cbranch_execnz .LBB0_1834

.LBB0_2222:
	s_mov_b64 s[12:13], s[74:75]
	s_waitcnt lgkmcnt(0)
	s_barrier
	v_mbcnt_lo_u32_b32 v0, -1, 0
	v_mbcnt_hi_u32_b32 v0, -1, v0
	v_readlane_b32 s2, v251, 5
	s_nop 1
	v_add_u32_e32 v0, s2, v0
	v_readlane_b32 s2, v251, 4
	s_nop 0
	v_ashrrev_i32_e32 v1, 6, v0
	v_add_u32_e32 v8, s2, v1
	s_movk_i32 s2, 0x200
	v_cmp_gt_i32_e32 vcc, s2, v8
	s_and_saveexec_b64 s[6:7], vcc
	s_cbranch_execz .LBB0_2241
	s_load_dwordx8 s[40:47], s[12:13], 0xf8
	v_readlane_b32 s2, v252, 14
	v_readlane_b32 s3, v252, 15
	s_and_b64 s[2:3], s[2:3], exec
	v_lshlrev_b32_e32 v0, 2, v0
	s_waitcnt lgkmcnt(0)
	s_cselect_b32 s17, 0, s45
	s_cselect_b32 s16, 0, s44
	s_lshl_b64 s[2:3], s[86:87], 2
	s_add_u32 s12, s42, s2
	s_addc_u32 s13, s43, s3
	v_and_b32_e32 v10, 0xfc, v0
	s_add_u32 s28, s40, s2
	v_lshlrev_b32_e32 v0, 2, v10
	v_mov_b32_e32 v1, v64
	v_lshlrev_b32_e32 v2, 1, v10
	v_mov_b32_e32 v3, v64
	s_addc_u32 s29, s41, s3
	v_lshl_add_u64 v[14:15], s[12:13], 0, v[0:1]
	v_lshl_add_u64 v[2:3], s[46:47], 0, v[2:3]
	s_mov_b64 s[12:13], 0x4000000
	s_cmp_lg_u64 s[16:17], 0
	v_lshl_add_u64 v[12:13], s[28:29], 0, v[0:1]
	v_lshl_add_u64 v[16:17], v[2:3], 0, s[12:13]
	v_lshl_add_u64 v[0:1], s[46:47], 0, v[0:1]
	s_mov_b64 s[12:13], 0x18500000
	s_mov_b64 s[2:3], 0
	s_cselect_b64 s[20:21], -1, 0
	v_lshl_add_u64 v[18:19], v[0:1], 0, s[12:13]
	global_load_dwordx4 v[164:167], v[12:13], off
	global_load_dwordx4 v[168:171], v[14:15], off
	global_load_dwordx4 v[172:175], v[12:13], off offset:1024
	global_load_dwordx4 v[176:179], v[14:15], off offset:1024
	global_load_dwordx4 v[180:183], v[12:13], off offset:2048
	global_load_dwordx4 v[184:187], v[14:15], off offset:2048
	global_load_dwordx4 v[188:191], v[12:13], off offset:3072
	global_load_dwordx4 v[192:195], v[14:15], off offset:3072
	s_branch .LBB0_2226

.LBB0_2226:
	v_ashrrev_i32_e32 v9, 31, v8
	s_mov_b64 s[12:13], 0x8000
	v_lshl_add_u64 v[4:5], v[8:9], 0, s[12:13]
	v_lshlrev_b64 v[0:1], 11, v[4:5]
	v_lshl_add_u64 v[20:21], v[16:17], 0, v[0:1]
	global_load_dwordx2 v[68:69], v[20:21], off
	v_lshlrev_b64 v[2:3], 12, v[8:9]
	v_lshl_add_u64 v[34:35], v[18:19], 0, v[2:3]
	global_load_dwordx4 v[72:75], v[34:35], off
	s_mov_b32 s12, 0x200000
	v_add_co_u32_e32 v32, vcc, s12, v34
	s_mov_b32 s12, 0x400000
	s_nop 0
	v_addc_co_u32_e32 v33, vcc, 0, v35, vcc
	global_load_dwordx4 v[76:79], v[32:33], off
	v_add_co_u32_e32 v40, vcc, s12, v34
	s_mov_b32 s12, 0x600000
	s_nop 0
	v_addc_co_u32_e32 v41, vcc, 0, v35, vcc
	global_load_dwordx4 v[80:83], v[40:41], off
	v_add_co_u32_e32 v44, vcc, s12, v34
	s_mov_b32 s29, 0x800000
	s_nop 0
	v_addc_co_u32_e32 v45, vcc, 0, v35, vcc
	global_load_dwordx4 v[84:87], v[44:45], off
	v_add_co_u32_e32 v42, vcc, s29, v34
	s_mov_b32 s12, 0xa00000
	s_nop 0
	v_addc_co_u32_e32 v43, vcc, 0, v35, vcc
	global_load_dwordx4 v[88:91], v[42:43], off
	v_add_co_u32_e32 v38, vcc, s12, v34
	s_mov_b32 s12, 0xc00000
	s_nop 0
	v_addc_co_u32_e32 v39, vcc, 0, v35, vcc
	global_load_dwordx4 v[92:95], v[38:39], off
	s_waitcnt vmcnt(6)
	v_lshlrev_b32_e32 v6, 16, v68
	v_and_b32_e32 v7, 0xffff0000, v68
	v_lshlrev_b32_e32 v22, 16, v69
	v_and_b32_e32 v23, 0xffff0000, v69
	s_waitcnt vmcnt(5)
	v_pk_fma_f32 v[22:23], v[22:23], s[94:95], v[74:75] op_sel_hi:[1,0,1]
	v_pk_fma_f32 v[6:7], v[6:7], s[94:95], v[72:73] op_sel_hi:[1,0,1]
	s_waitcnt vmcnt(4)
	v_pk_add_f32 v[22:23], v[22:23], v[78:79]
	v_pk_add_f32 v[6:7], v[6:7], v[76:77]
	s_waitcnt vmcnt(3)
	v_pk_add_f32 v[22:23], v[22:23], v[82:83]
	v_pk_add_f32 v[6:7], v[6:7], v[80:81]
	s_waitcnt vmcnt(2)
	v_pk_add_f32 v[22:23], v[22:23], v[86:87]
	v_pk_add_f32 v[6:7], v[6:7], v[84:85]
	s_waitcnt vmcnt(1)
	v_pk_add_f32 v[22:23], v[22:23], v[90:91]
	v_pk_add_f32 v[6:7], v[6:7], v[88:89]
	s_waitcnt vmcnt(0)
	v_pk_add_f32 v[26:27], v[22:23], v[94:95]
	v_add_co_u32_e32 v2, vcc, s12, v34
	v_pk_add_f32 v[0:1], v[6:7], v[92:93]
	s_nop 0
	v_addc_co_u32_e32 v3, vcc, 0, v35, vcc
	global_load_dwordx4 v[96:99], v[2:3], off
	s_mov_b32 s12, 0xe00000
	s_waitcnt vmcnt(0)
	v_pk_add_f32 v[6:7], v[26:27], v[98:99]
	v_pk_add_f32 v[26:27], v[0:1], v[96:97]
	v_add_co_u32_e32 v0, vcc, s12, v34
	s_nop 1
	v_addc_co_u32_e32 v1, vcc, 0, v35, vcc
	global_load_dwordx4 v[100:103], v[0:1], off
	global_load_dwordx2 v[104:105], v[20:21], off offset:512
	global_load_dwordx4 v[108:111], v[34:35], off offset:1024
	global_load_dwordx4 v[112:115], v[32:33], off offset:1024
	global_load_dwordx4 v[116:119], v[40:41], off offset:1024
	global_load_dwordx4 v[120:123], v[44:45], off offset:1024
	global_load_dwordx4 v[124:127], v[42:43], off offset:1024
	global_load_dwordx4 v[128:131], v[38:39], off offset:1024
	global_load_dwordx4 v[132:135], v[2:3], off offset:1024
	global_load_dwordx4 v[136:139], v[0:1], off offset:1024
	global_load_dwordx2 v[140:141], v[20:21], off offset:1024
	global_load_dwordx4 v[144:147], v[34:35], off offset:2048
	global_load_dwordx4 v[148:151], v[32:33], off offset:2048
	global_load_dwordx4 v[152:155], v[40:41], off offset:2048
	global_load_dwordx4 v[156:159], v[44:45], off offset:2048
	global_load_dwordx4 v[160:163], v[42:43], off offset:2048
	global_load_dwordx4 v[68:71], v[38:39], off offset:2048
	global_load_dwordx4 v[72:75], v[2:3], off offset:2048
	global_load_dwordx4 v[76:79], v[0:1], off offset:2048
	global_load_dwordx2 v[80:81], v[20:21], off offset:1536
	global_load_dwordx4 v[84:87], v[34:35], off offset:3072
	global_load_dwordx4 v[88:91], v[32:33], off offset:3072
	global_load_dwordx4 v[92:95], v[40:41], off offset:3072
	global_load_dwordx4 v[96:99], v[44:45], off offset:3072
	s_waitcnt vmcnt(23)
	v_pk_add_f32 v[30:31], v[26:27], v[100:101]
	v_pk_add_f32 v[6:7], v[6:7], v[102:103]
	global_load_dwordx4 v[100:103], v[42:43], off offset:3072
	s_waitcnt vmcnt(23)
	v_lshlrev_b32_e32 v26, 16, v104
	v_and_b32_e32 v27, 0xffff0000, v104
	v_lshlrev_b32_e32 v28, 16, v105
	v_and_b32_e32 v29, 0xffff0000, v105
	global_load_dwordx4 v[104:107], v[38:39], off offset:3072
	s_waitcnt vmcnt(23)
	v_pk_fma_f32 v[28:29], v[28:29], s[94:95], v[110:111] op_sel_hi:[1,0,1]
	v_pk_fma_f32 v[26:27], v[26:27], s[94:95], v[108:109] op_sel_hi:[1,0,1]
	global_load_dwordx4 v[108:111], v[2:3], off offset:3072
	s_waitcnt vmcnt(23)
	v_pk_add_f32 v[28:29], v[28:29], v[114:115]
	v_pk_add_f32 v[26:27], v[26:27], v[112:113]
	global_load_dwordx4 v[112:115], v[0:1], off offset:3072
	s_waitcnt vmcnt(23)
	v_pk_add_f32 v[28:29], v[28:29], v[118:119]
	v_pk_add_f32 v[26:27], v[26:27], v[116:117]
	s_waitcnt vmcnt(22)
	v_pk_add_f32 v[28:29], v[28:29], v[122:123]
	v_pk_add_f32 v[26:27], v[26:27], v[120:121]
	s_waitcnt vmcnt(21)
	v_pk_add_f32 v[28:29], v[28:29], v[126:127]
	v_pk_add_f32 v[26:27], v[26:27], v[124:125]
	s_waitcnt vmcnt(20)
	v_pk_add_f32 v[28:29], v[28:29], v[130:131]
	v_pk_add_f32 v[26:27], v[26:27], v[128:129]
	s_waitcnt vmcnt(19)
	v_pk_add_f32 v[28:29], v[28:29], v[134:135]
	v_pk_add_f32 v[36:37], v[26:27], v[132:133]
	s_waitcnt vmcnt(18)
	v_pk_add_f32 v[22:23], v[28:29], v[138:139]
	v_pk_mov_b32 v[26:27], v[30:31], v[6:7] op_sel:[1,0]
	v_mov_b32_e32 v28, v30
	v_mov_b32_e32 v29, v7
	v_pk_add_f32 v[26:27], v[26:27], v[28:29]
	v_pk_add_f32 v[24:25], v[36:37], v[136:137]
	v_add_f32_e32 v9, v26, v27
	v_add_f32_e32 v36, 0, v9
	s_waitcnt vmcnt(17)
	v_lshlrev_b32_e32 v46, 16, v140
	v_and_b32_e32 v47, 0xffff0000, v140
	v_lshlrev_b32_e32 v48, 16, v141
	v_and_b32_e32 v49, 0xffff0000, v141
	s_waitcnt vmcnt(16)
	v_pk_fma_f32 v[48:49], v[48:49], s[94:95], v[146:147] op_sel_hi:[1,0,1]
	v_pk_fma_f32 v[46:47], v[46:47], s[94:95], v[144:145] op_sel_hi:[1,0,1]
	s_waitcnt vmcnt(15)
	v_pk_add_f32 v[48:49], v[48:49], v[150:151]
	v_pk_add_f32 v[46:47], v[46:47], v[148:149]
	s_waitcnt vmcnt(14)
	v_pk_add_f32 v[48:49], v[48:49], v[154:155]
	v_pk_add_f32 v[46:47], v[46:47], v[152:153]
	s_waitcnt vmcnt(13)
	v_pk_add_f32 v[48:49], v[48:49], v[158:159]
	v_pk_add_f32 v[46:47], v[46:47], v[156:157]
	s_waitcnt vmcnt(12)
	v_pk_add_f32 v[48:49], v[48:49], v[162:163]
	v_pk_add_f32 v[46:47], v[46:47], v[160:161]
	s_waitcnt vmcnt(11)
	v_pk_add_f32 v[48:49], v[48:49], v[70:71]
	v_pk_add_f32 v[46:47], v[46:47], v[68:69]
	s_waitcnt vmcnt(10)
	v_pk_add_f32 v[28:29], v[48:49], v[74:75]
	v_pk_add_f32 v[50:51], v[46:47], v[72:73]
	s_waitcnt vmcnt(9)
	v_pk_add_f32 v[26:27], v[28:29], v[78:79]
	v_pk_add_f32 v[28:29], v[50:51], v[76:77]
	v_pk_mov_b32 v[46:47], v[24:25], v[22:23] op_sel:[1,0]
	v_mov_b32_e32 v48, v24
	v_mov_b32_e32 v49, v23
	v_pk_add_f32 v[46:47], v[46:47], v[48:49]
	s_waitcnt vmcnt(8)
	v_lshlrev_b32_e32 v54, 16, v80
	v_and_b32_e32 v55, 0xffff0000, v80
	v_lshlrev_b32_e32 v56, 16, v81
	v_and_b32_e32 v57, 0xffff0000, v81
	v_pk_add_f32 v[48:49], v[46:47], v[46:47] op_sel:[0,1] op_sel_hi:[1,0]
	v_add_f32_e32 v46, v26, v27
	s_waitcnt vmcnt(7)
	v_pk_fma_f32 v[52:53], v[56:57], s[94:95], v[86:87] op_sel_hi:[1,0,1]
	v_pk_fma_f32 v[50:51], v[54:55], s[94:95], v[84:85] op_sel_hi:[1,0,1]
	s_waitcnt vmcnt(6)
	v_pk_add_f32 v[52:53], v[52:53], v[90:91]
	v_pk_add_f32 v[50:51], v[50:51], v[88:89]
	s_waitcnt vmcnt(5)
	v_pk_add_f32 v[40:41], v[52:53], v[94:95]
	v_pk_add_f32 v[50:51], v[50:51], v[92:93]
	s_waitcnt vmcnt(4)
	v_pk_add_f32 v[40:41], v[40:41], v[98:99]
	v_pk_add_f32 v[44:45], v[50:51], v[96:97]
	s_waitcnt vmcnt(3)
	v_pk_add_f32 v[40:41], v[40:41], v[102:103]
	v_pk_add_f32 v[42:43], v[44:45], v[100:101]
	s_waitcnt vmcnt(2)
	v_pk_add_f32 v[34:35], v[40:41], v[106:107]
	v_pk_add_f32 v[42:43], v[42:43], v[104:105]
	s_waitcnt vmcnt(1)
	v_pk_add_f32 v[32:33], v[34:35], v[110:111]
	v_pk_add_f32 v[34:35], v[42:43], v[108:109]
	s_waitcnt vmcnt(0)
	v_pk_add_f32 v[32:33], v[32:33], v[114:115]
	v_pk_add_f32 v[34:35], v[34:35], v[112:113]
	v_add_f32_e32 v0, v28, v29
	v_mov_b32_e32 v37, v34
	v_mov_b32_e32 v49, v35
	v_mov_b32_e32 v1, v32
	v_mov_b32_e32 v47, v33
	v_pk_add_f32 v[2:3], v[36:37], v[48:49]
	v_pk_add_f32 v[0:1], v[0:1], v[46:47]
	s_nop 0
	v_pk_add_f32 v[0:1], v[2:3], v[0:1]
	s_nop 0
	v_add_f32_e32 v0, v0, v1
	s_nop 1
	v_add_f32_dpp v0, v0, v0 quad_perm:[1,0,3,2] row_mask:0xf bank_mask:0xf bound_ctrl:1
	s_nop 1
	v_add_f32_dpp v0, v0, v0 quad_perm:[2,3,0,1] row_mask:0xf bank_mask:0xf bound_ctrl:1
	s_nop 1
	v_add_f32_dpp v0, v0, v0 row_half_mirror row_mask:0xf bank_mask:0xf bound_ctrl:1
	s_nop 1
	v_add_f32_dpp v0, v0, v0 row_mirror row_mask:0xf bank_mask:0xf bound_ctrl:1
	s_nop 0
	v_readlane_b32 s18, v0, 16
	v_readlane_b32 s28, v0, 48
	v_readlane_b32 s12, v0, 0
	v_readlane_b32 s13, v0, 32
	v_mov_b32_e32 v0, s18
	v_mov_b32_e32 v1, s28
	v_pk_add_f32 v[0:1], s[12:13], v[0:1]
	s_nop 0
	v_add_f32_e32 v9, v0, v1
	v_fmamk_f32 v31, v9, 0xba800000, v31
	v_fmac_f32_e32 v30, 0xba800000, v9
	v_fmamk_f32 v7, v9, 0xba800000, v7
	v_fmac_f32_e32 v6, 0xba800000, v9
	v_pk_mul_f32 v[0:1], v[6:7], v[6:7]
	v_pk_mul_f32 v[2:3], v[30:31], v[30:31]
	v_fmamk_f32 v23, v9, 0xba800000, v23
	v_pk_mov_b32 v[36:37], v[2:3], v[0:1] op_sel:[1,0]
	v_mov_b32_e32 v3, v1
	v_pk_add_f32 v[0:1], v[36:37], v[2:3]
	v_fmac_f32_e32 v22, 0xba800000, v9
	v_fmamk_f32 v25, v9, 0xba800000, v25
	v_fmac_f32_e32 v24, 0xba800000, v9
	v_pk_add_f32 v[0:1], v[0:1], v[0:1] op_sel_hi:[0,1]
	v_pk_mul_f32 v[2:3], v[22:23], v[22:23]
	v_pk_mul_f32 v[36:37], v[24:25], v[24:25]
	v_fmac_f32_e32 v28, 0xba800000, v9
	v_pk_mov_b32 v[38:39], v[36:37], v[2:3] op_sel:[1,0]
	v_mov_b32_e32 v37, v3
	v_fmac_f32_e32 v26, 0xba800000, v9
	v_fmamk_f32 v29, v9, 0xba800000, v29
	v_mul_f32_e32 v0, v28, v28
	v_pk_add_f32 v[2:3], v[38:39], v[36:37]
	v_fmamk_f32 v27, v9, 0xba800000, v27
	v_pk_fma_f32 v[36:37], v[28:29], v[28:29], v[0:1] op_sel_hi:[1,1,0]
	v_mul_f32_e32 v0, v26, v26
	v_pk_add_f32 v[2:3], v[2:3], v[2:3] op_sel_hi:[0,1]
	v_pk_fma_f32 v[38:39], v[26:27], v[26:27], v[0:1] op_sel_hi:[1,1,0]
	v_fmamk_f32 v33, v9, 0xba800000, v33
	v_fmac_f32_e32 v32, 0xba800000, v9
	v_fmamk_f32 v35, v9, 0xba800000, v35
	v_fmac_f32_e32 v34, 0xba800000, v9
	v_mul_f32_e32 v36, v34, v34
	v_mul_f32_e32 v38, v35, v35
	v_mul_f32_e32 v0, v32, v32
	v_mul_f32_e32 v2, v33, v33
	v_pk_add_f32 v[36:37], v[36:37], v[38:39]
	v_pk_add_f32 v[0:1], v[0:1], v[2:3]
	s_nop 0
	v_pk_add_f32 v[0:1], v[36:37], v[0:1]
	s_nop 0
	v_add_f32_e32 v0, v0, v1
	s_nop 1
	v_add_f32_dpp v0, v0, v0 quad_perm:[1,0,3,2] row_mask:0xf bank_mask:0xf bound_ctrl:1
	s_nop 1
	v_add_f32_dpp v0, v0, v0 quad_perm:[2,3,0,1] row_mask:0xf bank_mask:0xf bound_ctrl:1
	s_nop 1
	v_add_f32_dpp v0, v0, v0 row_half_mirror row_mask:0xf bank_mask:0xf bound_ctrl:1
	s_nop 1
	v_add_f32_dpp v0, v0, v0 row_mirror row_mask:0xf bank_mask:0xf bound_ctrl:1
	s_nop 0
	v_readlane_b32 s18, v0, 16
	v_readlane_b32 s28, v0, 48
	v_readlane_b32 s12, v0, 0
	v_readlane_b32 s13, v0, 32
	v_mov_b32_e32 v0, s18
	v_mov_b32_e32 v1, s28
	v_pk_add_f32 v[0:1], s[12:13], v[0:1]
	s_nop 0
	v_add_f32_e32 v0, v0, v1
	v_fmamk_f32 v0, v0, 0x3a800000, v213
	v_cmp_gt_f32_e32 vcc, s29, v0
	v_mul_f32_e32 v1, 0x4b800000, v0
	s_nop 0
	v_cndmask_b32_e32 v0, v0, v1, vcc
	v_rsq_f32_e32 v0, v0
	s_nop 0
	v_mul_f32_e32 v1, 0x45800000, v0
	v_cndmask_b32_e32 v38, v0, v1, vcc
	v_lshlrev_b64 v[0:1], 12, v[4:5]
	v_lshl_add_u64 v[36:37], s[16:17], 0, v[0:1]
	v_pk_mul_f32 v[40:41], v[6:7], v[38:39] op_sel_hi:[1,0]


	v_pk_mul_f32 v[30:31], v[30:31], v[38:39] op_sel_hi:[1,0]
	s_andn2_b64 vcc, exec, s[20:21]
	s_waitcnt vmcnt(0)
	v_pk_fma_f32 v[0:1], v[164:165], v[30:31], v[168:169]
	v_cndmask_b32_e64 v4, 0, 1, s[20:21]
	v_pk_fma_f32 v[2:3], v[166:167], v[40:41], v[170:171]
	v_cmp_ne_u32_e64 s[40:41], 1, v4
	v_lshlrev_b32_e32 v4, 2, v10
	s_cbranch_vccnz .LBB0_2237
	v_mov_b32_e32 v5, v64
	v_lshl_add_u64 v[6:7], v[36:37], 0, v[4:5]
	global_store_dwordx4 v[6:7], v[0:3], off
	s_cbranch_execnz .LBB0_2229

.LBB0_2229:
	v_mov_b32_e32 v39, v38
	v_mov_b32_e32 v0, v38
	v_mov_b32_e32 v1, v38
	v_pk_mul_f32 v[6:7], v[22:23], v[0:1]
	v_pk_mul_f32 v[30:31], v[24:25], v[38:39]


	s_and_b64 vcc, exec, s[40:41]

	v_pk_fma_f32 v[2:3], v[6:7], v[174:175], v[178:179]
	v_pk_fma_f32 v[0:1], v[30:31], v[172:173], v[176:177]
	s_cbranch_vccnz .LBB0_2238
	v_mov_b32_e32 v5, v64
	v_lshl_add_u64 v[6:7], v[36:37], 0, v[4:5]
	global_store_dwordx4 v[6:7], v[0:3], off offset:1024
	s_cbranch_execnz .LBB0_2232

.LBB0_2232:
	s_nop 0
	v_mov_b32_e32 v0, v38
	v_mov_b32_e32 v1, v38
	v_pk_mul_f32 v[6:7], v[26:27], v[0:1]


	v_pk_mul_f32 v[26:27], v[28:29], v[38:39]
	s_and_b64 vcc, exec, s[40:41]

	v_pk_fma_f32 v[2:3], v[6:7], v[182:183], v[186:187]
	v_pk_fma_f32 v[0:1], v[26:27], v[180:181], v[184:185]
	s_cbranch_vccnz .LBB0_2239
	v_mov_b32_e32 v5, v64
	v_lshl_add_u64 v[6:7], v[36:37], 0, v[4:5]
	global_store_dwordx4 v[6:7], v[0:3], off offset:2048
	s_cbranch_execnz .LBB0_2235

.LBB0_2235:
	s_nop 0
	v_mov_b32_e32 v0, v38
	v_mov_b32_e32 v1, v38
	v_pk_mul_f32 v[6:7], v[32:33], v[0:1]


	v_pk_mul_f32 v[26:27], v[34:35], v[38:39]
	s_and_b64 vcc, exec, s[40:41]

	v_pk_fma_f32 v[2:3], v[6:7], v[190:191], v[194:195]
	v_pk_fma_f32 v[0:1], v[26:27], v[188:189], v[192:193]
	s_cbranch_vccnz .LBB0_2240
	v_mov_b32_e32 v5, v64
	v_lshl_add_u64 v[4:5], v[36:37], 0, v[4:5]
	global_store_dwordx4 v[4:5], v[0:3], off offset:3072
	s_cbranch_execnz .LBB0_2225
	s_branch .LBB0_2224
